# chanmix W2 tile load loop fully unrolled (8 loads in flight instead of 8 dependent load-wait-write rounds), both even layers; on top of the k=S/2 row unroll
# baseline (speedup 1.0000x reference)
; #define LAS __attribute__((address_space(3)))
; __device__ __forceinline__ void chanmix_phase(const Params& p, LAS unsigned char* lds, int li, int tid, int G, bf16_t* dst) {
;     ...
;         if (g != curg) {
;             __syncthreads();
;             const bf16_t* W2 = (const bf16_t*)(ws + OFF_W2) + (size_t)(li * 4 + g) * 128 * 256;
;             for (int q = tid; q < 4096; q += 512) { const int row = q >> 5, c16 = q & 31; *(LAS u32x4*)(lds + row * 528 + c16 * 16) = *(const u32x4*)(W2 + row * 256 + c16 * 8); }
;             __syncthreads();
.LBB0_559:
	v_ashrrev_i32_e32 v35, 5, v34
	v_lshlrev_b32_e32 v36, 8, v35
	v_ashrrev_i32_e32 v37, 31, v36
	v_lshl_add_u64 v[152:153], v[36:37], 1, v[32:33]
	v_mad_u64_u32 v[40:41], s[18:19], v35, s0, v[82:83]
	s_mov_b64 s[50:51], 0x2000
	global_load_dwordx4 v[120:123], v[152:153], off
	v_lshl_add_u64 v[152:153], v[152:153], 0, s[50:51]
	global_load_dwordx4 v[124:127], v[152:153], off
	v_lshl_add_u64 v[152:153], v[152:153], 0, s[50:51]
	global_load_dwordx4 v[128:131], v[152:153], off
	v_lshl_add_u64 v[152:153], v[152:153], 0, s[50:51]
	global_load_dwordx4 v[132:135], v[152:153], off
	v_lshl_add_u64 v[152:153], v[152:153], 0, s[50:51]
	global_load_dwordx4 v[136:139], v[152:153], off
	v_lshl_add_u64 v[152:153], v[152:153], 0, s[50:51]
	global_load_dwordx4 v[140:143], v[152:153], off
	v_lshl_add_u64 v[152:153], v[152:153], 0, s[50:51]
	global_load_dwordx4 v[144:147], v[152:153], off
	v_lshl_add_u64 v[152:153], v[152:153], 0, s[50:51]
	global_load_dwordx4 v[148:151], v[152:153], off
	s_waitcnt vmcnt(7)
	ds_write_b128 v40, v[120:123]
	s_waitcnt vmcnt(6)
	ds_write_b128 v40, v[124:127] offset:8448
	s_waitcnt vmcnt(5)
	ds_write_b128 v40, v[128:131] offset:16896
	s_waitcnt vmcnt(4)
	ds_write_b128 v40, v[132:135] offset:25344
	s_waitcnt vmcnt(3)
	ds_write_b128 v40, v[136:139] offset:33792
	s_waitcnt vmcnt(2)
	ds_write_b128 v40, v[140:143] offset:42240
	s_waitcnt vmcnt(1)
	ds_write_b128 v40, v[144:147] offset:50688
	s_waitcnt vmcnt(0)
	ds_write_b128 v40, v[148:151] offset:59136

; #define LAS __attribute__((address_space(3)))
; __device__ __forceinline__ void chanmix_phase(const Params& p, LAS unsigned char* lds, int li, int tid, int G, bf16_t* dst) {
;     ...
;         if (g != curg) {
;             __syncthreads();
;             const bf16_t* W2 = (const bf16_t*)(ws + OFF_W2) + (size_t)(li * 4 + g) * 128 * 256;
;             for (int q = tid; q < 4096; q += 512) { const int row = q >> 5, c16 = q & 31; *(LAS u32x4*)(lds + row * 528 + c16 * 16) = *(const u32x4*)(W2 + row * 256 + c16 * 8); }
;             __syncthreads();
.LBB0_1312:
	v_ashrrev_i32_e32 v35, 5, v34
	v_lshlrev_b32_e32 v36, 8, v35
	v_ashrrev_i32_e32 v37, 31, v36
	v_lshl_add_u64 v[152:153], v[36:37], 1, v[32:33]
	v_mad_u64_u32 v[40:41], s[14:15], v35, s0, v[82:83]
	s_mov_b64 s[50:51], 0x2000
	global_load_dwordx4 v[120:123], v[152:153], off
	v_lshl_add_u64 v[152:153], v[152:153], 0, s[50:51]
	global_load_dwordx4 v[124:127], v[152:153], off
	v_lshl_add_u64 v[152:153], v[152:153], 0, s[50:51]
	global_load_dwordx4 v[128:131], v[152:153], off
	v_lshl_add_u64 v[152:153], v[152:153], 0, s[50:51]
	global_load_dwordx4 v[132:135], v[152:153], off
	v_lshl_add_u64 v[152:153], v[152:153], 0, s[50:51]
	global_load_dwordx4 v[136:139], v[152:153], off
	v_lshl_add_u64 v[152:153], v[152:153], 0, s[50:51]
	global_load_dwordx4 v[140:143], v[152:153], off
	v_lshl_add_u64 v[152:153], v[152:153], 0, s[50:51]
	global_load_dwordx4 v[144:147], v[152:153], off
	v_lshl_add_u64 v[152:153], v[152:153], 0, s[50:51]
	global_load_dwordx4 v[148:151], v[152:153], off
	s_waitcnt vmcnt(7)
	ds_write_b128 v40, v[120:123]
	s_waitcnt vmcnt(6)
	ds_write_b128 v40, v[124:127] offset:8448
	s_waitcnt vmcnt(5)
	ds_write_b128 v40, v[128:131] offset:16896
	s_waitcnt vmcnt(4)
	ds_write_b128 v40, v[132:135] offset:25344
	s_waitcnt vmcnt(3)
	ds_write_b128 v40, v[136:139] offset:33792
	s_waitcnt vmcnt(2)
	ds_write_b128 v40, v[140:143] offset:42240
	s_waitcnt vmcnt(1)
	ds_write_b128 v40, v[144:147] offset:50688
	s_waitcnt vmcnt(0)
	ds_write_b128 v40, v[148:151] offset:59136
